# sample K/V cache conversion moved whole to after FFN-up (160 idle workgroups) instead of after FFN-down
# speedup vs baseline: 1.0136x; 1.0013x over previous
.LBB0_1197:
	v_readlane_b32 s0, v255, 16
	v_readlane_b32 s1, v255, 17
	s_andn2_b64 vcc, exec, s[0:1]
	s_cbranch_vccnz .Lpc_done
	s_sub_i32 s2, s92, 0x60
	s_cmp_lt_i32 s2, 0
	s_cbranch_scc1 .Lpc_done
	s_movk_i32 s14, 0xa0
	s_mov_b64 s[98:99], s[8:9]
	v_readlane_b32 s8, v255, 2
	v_readlane_b32 s9, v255, 3
	v_mbcnt_lo_u32_b32 v0, -1, 0
	v_mbcnt_hi_u32_b32 v0, -1, v0
	v_readlane_b32 s0, v255, 4
	s_lshl_b32 s10, s2, 5
	s_nop 0
	v_or_b32_e32 v0, s0, v0
	s_nop 0
	v_readfirstlane_b32 s0, v0
	s_ashr_i32 s0, s0, 4
	s_and_b32 s11, s0, -4
	s_add_i32 s0, s11, s10
	s_cmp_gt_i32 s0, 0xffff
	v_mbcnt_lo_u32_b32 v0, -1, 0
	v_mbcnt_hi_u32_b32 v0, -1, v0
	s_cbranch_scc1 .Lpc_restore
	s_load_dwordx2 s[2:3], s[8:9], 0x108
	s_load_dwordx4 s[4:7], s[8:9], 0x30
	v_readlane_b32 s8, v255, 14
	v_lshlrev_b32_e32 v0, 3, v0
	v_and_b32_e32 v12, 0x1f8, v0
	s_waitcnt lgkmcnt(0)
	s_add_u32 s0, s2, 0x50c00000
	s_addc_u32 s1, s3, 0
	s_add_u32 s2, s2, 0x55400000
	s_addc_u32 s3, s3, 0
	s_add_i32 s8, s8, s10
	s_lshl_b32 s15, s54, 16
	s_lshl_b32 s14, s14, 5
	s_add_i32 s20, s8, s11
	s_add_i32 s15, s15, 0x10000
	s_ashr_i32 s21, s20, 31
	s_ashr_i32 s22, s14, 31

.Lpc_restore:
	s_mov_b64 s[8:9], s[98:99]

.LBB0_1289:
	s_lshl_b32 s80, s96, 8
	s_ashr_i32 s81, s80, 31
	s_lshl_b64 s[86:87], s[80:81], 2
	s_add_u32 s84, s84, s86
	s_addc_u32 s85, s85, s87
	s_add_i32 m0, s94, s41
	s_add_u32 s81, s82, 0x100
	global_load_lds_dwordx4 v239, s[84:85]
	s_addc_u32 s96, s83, 0
	s_cmp_eq_u32 s54, 5
	s_cselect_b32 vcc_lo, 66, -2
	s_bfe_u32 s86, s1, 0x20003
	s_cmp_eq_u32 s86, 3
	s_cselect_b32 s86, -8, 0
	s_cmp_eq_u32 s54, 5
	s_cselect_b32 s86, s86, 0
	s_add_i32 vcc_lo, vcc_lo, s86
	s_add_u32 s82, s78, 0x100
	s_addc_u32 s83, s79, 0
	s_add_i32 s94, 0, 0x10000
	s_cmpk_eq_i32 vcc_lo, 0x54
	s_cselect_b32 s87, s75, s83
	s_cselect_b32 s86, s74, s82
	s_cselect_b32 s85, s77, s96
	s_cselect_b32 s84, s76, s81
	s_add_i32 vcc_hi, 0, 0x14000
	v_add_u32_e32 v96, s94, v238
	v_add_u32_e32 v140, vcc_hi, v238
	ds_read_b128 v[64:67], v96
	ds_read_b128 v[72:75], v96 offset:1024
	ds_read_b128 v[88:91], v96 offset:2048
	ds_read_b128 v[96:99], v96 offset:3072
	ds_read_b128 v[108:111], v140
	ds_read_b128 v[116:119], v140 offset:1024
	ds_read_b128 v[128:131], v140 offset:2048
	ds_read_b128 v[140:143], v140 offset:3072
	v_lshl_add_u64 v[192:193], s[78:79], 0, v[230:231]
	s_add_i32 m0, s29, 0xc000
	ds_read_b128 v[152:155], v240
	ds_read_b128 v[156:159], v240 offset:1024
	ds_read_b128 v[160:163], v240 offset:2048
	ds_read_b128 v[164:167], v240 offset:3072
	ds_read_b128 v[168:171], v240 offset:4096
	ds_read_b128 v[180:183], v240 offset:5120
	ds_read_b128 v[184:187], v240 offset:6144
	ds_read_b128 v[188:191], v240 offset:7168
	global_load_lds_dwordx4 v[192:193], off
	v_lshl_add_u64 v[192:193], s[78:79], 0, v[232:233]
	s_add_i32 m0, s29, 0xe000
	s_nop 0
	global_load_lds_dwordx4 v[192:193], off
	s_waitcnt vmcnt(8)
	s_waitcnt lgkmcnt(0)
	s_barrier
	s_waitcnt lgkmcnt(0)
	v_mfma_f32_16x16x32_bf16 v[176:179], v[64:67], v[152:155], 0
	v_mfma_f32_16x16x32_bf16 v[172:175], v[88:91], v[152:155], 0
	v_mfma_f32_16x16x32_bf16 v[136:139], v[64:67], v[160:163], 0
	v_mfma_f32_16x16x32_bf16 v[132:135], v[88:91], v[160:163], 0
	v_mfma_f32_16x16x32_bf16 v[112:115], v[64:67], v[168:171], 0
	v_mfma_f32_16x16x32_bf16 v[104:107], v[88:91], v[168:171], 0
	v_mfma_f32_16x16x32_bf16 v[84:87], v[64:67], v[184:187], 0
	v_mfma_f32_16x16x32_bf16 v[80:83], v[88:91], v[184:187], 0
	v_mfma_f32_16x16x32_bf16 v[176:179], v[72:75], v[156:159], v[176:179]
	v_mfma_f32_16x16x32_bf16 v[172:175], v[96:99], v[156:159], v[172:175]
	v_mfma_f32_16x16x32_bf16 v[136:139], v[72:75], v[164:167], v[136:139]
	v_mfma_f32_16x16x32_bf16 v[132:135], v[96:99], v[164:167], v[132:135]
	v_mfma_f32_16x16x32_bf16 v[112:115], v[72:75], v[180:183], v[112:115]
	v_mfma_f32_16x16x32_bf16 v[104:107], v[96:99], v[180:183], v[104:107]
	v_mfma_f32_16x16x32_bf16 v[84:87], v[72:75], v[188:191], v[84:87]
	v_mfma_f32_16x16x32_bf16 v[80:83], v[96:99], v[188:191], v[80:83]
	v_mfma_f32_16x16x32_bf16 v[148:151], v[108:111], v[152:155], 0
	v_mfma_f32_16x16x32_bf16 v[144:147], v[128:131], v[152:155], 0
	v_mfma_f32_16x16x32_bf16 v[124:127], v[108:111], v[160:163], 0
	v_mfma_f32_16x16x32_bf16 v[120:123], v[128:131], v[160:163], 0
	v_mfma_f32_16x16x32_bf16 v[100:103], v[108:111], v[168:171], 0
	v_mfma_f32_16x16x32_bf16 v[92:95], v[128:131], v[168:171], 0
	v_mfma_f32_16x16x32_bf16 v[76:79], v[108:111], v[184:187], 0
	v_mfma_f32_16x16x32_bf16 v[68:71], v[128:131], v[184:187], 0
	v_mfma_f32_16x16x32_bf16 v[148:151], v[116:119], v[156:159], v[148:151]
	v_mfma_f32_16x16x32_bf16 v[144:147], v[140:143], v[156:159], v[144:147]
	v_mfma_f32_16x16x32_bf16 v[124:127], v[116:119], v[164:167], v[124:127]
	v_mfma_f32_16x16x32_bf16 v[120:123], v[140:143], v[164:167], v[120:123]
	v_mfma_f32_16x16x32_bf16 v[100:103], v[116:119], v[180:183], v[100:103]
	v_mfma_f32_16x16x32_bf16 v[92:95], v[140:143], v[180:183], v[92:95]
	v_mfma_f32_16x16x32_bf16 v[76:79], v[116:119], v[188:191], v[76:79]
	v_mfma_f32_16x16x32_bf16 v[68:71], v[140:143], v[188:191], v[68:71]
	s_barrier
	s_add_i32 s78, s94, s2
	v_lshl_add_u64 v[192:193], s[84:85], 0, v[216:217]
	s_mov_b32 m0, s78
	ds_read_b128 v[152:155], v240 offset:16384
	ds_read_b128 v[156:159], v240 offset:17408
	ds_read_b128 v[160:163], v240 offset:18432
	ds_read_b128 v[164:167], v240 offset:19456
	ds_read_b128 v[168:171], v240 offset:20480
	ds_read_b128 v[180:183], v240 offset:21504
	ds_read_b128 v[184:187], v240 offset:22528
	ds_read_b128 v[188:191], v240 offset:23552
	global_load_lds_dwordx4 v[192:193], off
	s_add_i32 m0, s78, 0x2000
	s_add_u32 s78, s84, 0x160000
	v_lshl_add_u64 v[194:195], s[84:85], 0, v[228:229]
	s_addc_u32 s79, s85, 0
	s_add_i32 s94, vcc_hi, s2
	global_load_lds_dwordx4 v[194:195], off
	v_lshl_add_u64 v[196:197], s[78:79], 0, v[216:217]
	s_mov_b32 m0, s94
	v_lshl_add_u64 v[198:199], s[86:87], 0, v[226:227]
	global_load_lds_dwordx4 v[196:197], off
	v_lshl_add_u64 v[196:197], s[78:79], 0, v[228:229]
	s_add_i32 m0, s94, 0x2000
	s_nop 0
	global_load_lds_dwordx4 v[196:197], off
	v_lshl_add_u64 v[196:197], s[86:87], 0, v[224:225]
	s_mov_b32 m0, s29
	s_nop 0
	global_load_lds_dwordx4 v[196:197], off
	s_mov_b32 m0, s34
	s_nop 0
	global_load_lds_dwordx4 v[198:199], off
	s_waitcnt vmcnt(8)
	s_waitcnt lgkmcnt(0)
	s_barrier
	s_waitcnt lgkmcnt(0)
	v_mfma_f32_16x16x32_bf16 v[60:63], v[64:67], v[152:155], 0
	v_mfma_f32_16x16x32_bf16 v[56:59], v[88:91], v[152:155], 0
	v_mfma_f32_16x16x32_bf16 v[44:47], v[64:67], v[160:163], 0
	v_mfma_f32_16x16x32_bf16 v[40:43], v[88:91], v[160:163], 0
	v_mfma_f32_16x16x32_bf16 v[28:31], v[64:67], v[168:171], 0
	v_mfma_f32_16x16x32_bf16 v[24:27], v[88:91], v[168:171], 0
	v_mfma_f32_16x16x32_bf16 v[12:15], v[64:67], v[184:187], 0
	v_mfma_f32_16x16x32_bf16 v[8:11], v[88:91], v[184:187], 0
	v_mfma_f32_16x16x32_bf16 v[60:63], v[72:75], v[156:159], v[60:63]
	v_mfma_f32_16x16x32_bf16 v[56:59], v[96:99], v[156:159], v[56:59]
	v_mfma_f32_16x16x32_bf16 v[44:47], v[72:75], v[164:167], v[44:47]
	v_mfma_f32_16x16x32_bf16 v[40:43], v[96:99], v[164:167], v[40:43]
	v_mfma_f32_16x16x32_bf16 v[28:31], v[72:75], v[180:183], v[28:31]
	v_mfma_f32_16x16x32_bf16 v[24:27], v[96:99], v[180:183], v[24:27]
	v_mfma_f32_16x16x32_bf16 v[12:15], v[72:75], v[188:191], v[12:15]
	v_mfma_f32_16x16x32_bf16 v[8:11], v[96:99], v[188:191], v[8:11]
	v_mfma_f32_16x16x32_bf16 v[52:55], v[108:111], v[152:155], 0
	v_mfma_f32_16x16x32_bf16 v[48:51], v[128:131], v[152:155], 0
	v_mfma_f32_16x16x32_bf16 v[36:39], v[108:111], v[160:163], 0
	v_mfma_f32_16x16x32_bf16 v[32:35], v[128:131], v[160:163], 0
	v_mfma_f32_16x16x32_bf16 v[20:23], v[108:111], v[168:171], 0
	v_mfma_f32_16x16x32_bf16 v[16:19], v[128:131], v[168:171], 0
	v_mfma_f32_16x16x32_bf16 v[4:7], v[108:111], v[184:187], 0
	v_mfma_f32_16x16x32_bf16 v[0:3], v[128:131], v[184:187], 0
	v_mfma_f32_16x16x32_bf16 v[52:55], v[116:119], v[156:159], v[52:55]
	v_mfma_f32_16x16x32_bf16 v[48:51], v[140:143], v[156:159], v[48:51]
	v_mfma_f32_16x16x32_bf16 v[36:39], v[116:119], v[164:167], v[36:39]
	v_mfma_f32_16x16x32_bf16 v[32:35], v[140:143], v[164:167], v[32:35]
	v_mfma_f32_16x16x32_bf16 v[20:23], v[116:119], v[180:183], v[20:23]
	v_mfma_f32_16x16x32_bf16 v[16:19], v[140:143], v[180:183], v[16:19]
	v_mfma_f32_16x16x32_bf16 v[4:7], v[116:119], v[188:191], v[4:7]
	v_mfma_f32_16x16x32_bf16 v[0:3], v[140:143], v[188:191], v[0:3]
	s_barrier
	s_add_i32 s94, 0, 0x18000
	s_add_i32 vcc_hi, 0, 0x1c000
	v_add_u32_e32 v96, s94, v238
	v_add_u32_e32 v140, vcc_hi, v238
	ds_read_b128 v[64:67], v96
	ds_read_b128 v[72:75], v96 offset:1024
	ds_read_b128 v[88:91], v96 offset:2048
	ds_read_b128 v[96:99], v96 offset:3072
	ds_read_b128 v[108:111], v140
	ds_read_b128 v[116:119], v140 offset:1024
	ds_read_b128 v[128:131], v140 offset:2048
	ds_read_b128 v[140:143], v140 offset:3072
	s_add_u32 s78, s86, 0x160000
	s_addc_u32 s79, s87, 0
	s_mov_b32 m0, s35
	v_lshl_add_u64 v[200:201], s[78:79], 0, v[224:225]
	ds_read_b128 v[152:155], v240 offset:32768
	ds_read_b128 v[156:159], v240 offset:33792
	ds_read_b128 v[160:163], v240 offset:34816
	ds_read_b128 v[164:167], v240 offset:35840
	ds_read_b128 v[168:171], v240 offset:36864
	ds_read_b128 v[180:183], v240 offset:37888
	ds_read_b128 v[184:187], v240 offset:38912
	ds_read_b128 v[188:191], v240 offset:39936
	global_load_lds_dwordx4 v[200:201], off
	v_lshl_add_u64 v[200:201], s[78:79], 0, v[226:227]
	s_mov_b32 m0, s38
	s_nop 0
	global_load_lds_dwordx4 v[200:201], off
	s_waitcnt vmcnt(8)
	s_waitcnt lgkmcnt(0)
	s_barrier
	s_waitcnt lgkmcnt(0)
	v_mfma_f32_16x16x32_bf16 v[176:179], v[64:67], v[152:155], v[176:179]
	v_mfma_f32_16x16x32_bf16 v[172:175], v[88:91], v[152:155], v[172:175]
	v_mfma_f32_16x16x32_bf16 v[136:139], v[64:67], v[160:163], v[136:139]
	v_mfma_f32_16x16x32_bf16 v[132:135], v[88:91], v[160:163], v[132:135]
	v_mfma_f32_16x16x32_bf16 v[112:115], v[64:67], v[168:171], v[112:115]
	v_mfma_f32_16x16x32_bf16 v[104:107], v[88:91], v[168:171], v[104:107]
	v_mfma_f32_16x16x32_bf16 v[84:87], v[64:67], v[184:187], v[84:87]
	v_mfma_f32_16x16x32_bf16 v[80:83], v[88:91], v[184:187], v[80:83]
	v_mfma_f32_16x16x32_bf16 v[176:179], v[72:75], v[156:159], v[176:179]
	v_mfma_f32_16x16x32_bf16 v[172:175], v[96:99], v[156:159], v[172:175]
	v_mfma_f32_16x16x32_bf16 v[136:139], v[72:75], v[164:167], v[136:139]
	v_mfma_f32_16x16x32_bf16 v[132:135], v[96:99], v[164:167], v[132:135]
	v_mfma_f32_16x16x32_bf16 v[112:115], v[72:75], v[180:183], v[112:115]
	v_mfma_f32_16x16x32_bf16 v[104:107], v[96:99], v[180:183], v[104:107]
	v_mfma_f32_16x16x32_bf16 v[84:87], v[72:75], v[188:191], v[84:87]
	v_mfma_f32_16x16x32_bf16 v[80:83], v[96:99], v[188:191], v[80:83]
	v_mfma_f32_16x16x32_bf16 v[148:151], v[108:111], v[152:155], v[148:151]
	v_mfma_f32_16x16x32_bf16 v[144:147], v[128:131], v[152:155], v[144:147]
	v_mfma_f32_16x16x32_bf16 v[124:127], v[108:111], v[160:163], v[124:127]
	v_mfma_f32_16x16x32_bf16 v[120:123], v[128:131], v[160:163], v[120:123]
	v_mfma_f32_16x16x32_bf16 v[100:103], v[108:111], v[168:171], v[100:103]
	v_mfma_f32_16x16x32_bf16 v[92:95], v[128:131], v[168:171], v[92:95]
	v_mfma_f32_16x16x32_bf16 v[76:79], v[108:111], v[184:187], v[76:79]
	v_mfma_f32_16x16x32_bf16 v[68:71], v[128:131], v[184:187], v[68:71]
	v_mfma_f32_16x16x32_bf16 v[148:151], v[116:119], v[156:159], v[148:151]
	v_mfma_f32_16x16x32_bf16 v[144:147], v[140:143], v[156:159], v[144:147]
	v_mfma_f32_16x16x32_bf16 v[124:127], v[116:119], v[164:167], v[124:127]
	v_mfma_f32_16x16x32_bf16 v[120:123], v[140:143], v[164:167], v[120:123]
	v_mfma_f32_16x16x32_bf16 v[100:103], v[116:119], v[180:183], v[100:103]
	v_mfma_f32_16x16x32_bf16 v[92:95], v[140:143], v[180:183], v[92:95]
	v_mfma_f32_16x16x32_bf16 v[76:79], v[116:119], v[188:191], v[76:79]
	v_mfma_f32_16x16x32_bf16 v[68:71], v[140:143], v[188:191], v[68:71]
	s_barrier
	s_add_i32 s78, s94, s2
	v_lshl_add_u64 v[192:193], v[192:193], 0, s[30:31]
	s_mov_b32 m0, s78
	ds_read_b128 v[152:155], v240 offset:49152
	ds_read_b128 v[156:159], v240 offset:50176
	ds_read_b128 v[160:163], v240 offset:51200
	ds_read_b128 v[164:167], v240 offset:52224
	ds_read_b128 v[168:171], v240 offset:53248
	ds_read_b128 v[180:183], v240 offset:54272
	ds_read_b128 v[184:187], v240 offset:55296
	ds_read_b128 v[188:191], v240 offset:56320
	global_load_lds_dwordx4 v[192:193], off
	s_add_i32 m0, s78, 0x2000
	s_add_u32 s78, s84, 0x160080
	v_lshl_add_u64 v[192:193], v[194:195], 0, s[30:31]
	s_addc_u32 s79, s85, 0
	s_add_i32 s84, vcc_hi, s2
	global_load_lds_dwordx4 v[192:193], off
	v_lshl_add_u64 v[192:193], s[78:79], 0, v[216:217]
	s_mov_b32 m0, s84
	s_nop 0
	global_load_lds_dwordx4 v[192:193], off
	v_lshl_add_u64 v[192:193], s[78:79], 0, v[228:229]
	s_add_i32 m0, s84, 0x2000
	s_nop 0
	global_load_lds_dwordx4 v[192:193], off
	v_lshl_add_u64 v[192:193], v[196:197], 0, s[30:31]
	s_mov_b32 m0, s60
	s_nop 0
	global_load_lds_dwordx4 v[192:193], off
	v_lshl_add_u64 v[192:193], v[198:199], 0, s[30:31]
	s_mov_b32 m0, s61
	s_nop 0
	global_load_lds_dwordx4 v[192:193], off
	s_waitcnt vmcnt(8)
	s_waitcnt lgkmcnt(0)
	s_barrier
	s_waitcnt lgkmcnt(0)
	v_mfma_f32_16x16x32_bf16 v[60:63], v[64:67], v[152:155], v[60:63]
	v_mfma_f32_16x16x32_bf16 v[56:59], v[88:91], v[152:155], v[56:59]
	v_mfma_f32_16x16x32_bf16 v[44:47], v[64:67], v[160:163], v[44:47]
	v_mfma_f32_16x16x32_bf16 v[40:43], v[88:91], v[160:163], v[40:43]
	v_mfma_f32_16x16x32_bf16 v[28:31], v[64:67], v[168:171], v[28:31]
	v_mfma_f32_16x16x32_bf16 v[24:27], v[88:91], v[168:171], v[24:27]
	v_mfma_f32_16x16x32_bf16 v[12:15], v[64:67], v[184:187], v[12:15]
	v_mfma_f32_16x16x32_bf16 v[8:11], v[88:91], v[184:187], v[8:11]
	v_mfma_f32_16x16x32_bf16 v[60:63], v[72:75], v[156:159], v[60:63]
	v_mfma_f32_16x16x32_bf16 v[56:59], v[96:99], v[156:159], v[56:59]
	v_mfma_f32_16x16x32_bf16 v[44:47], v[72:75], v[164:167], v[44:47]
	v_mfma_f32_16x16x32_bf16 v[40:43], v[96:99], v[164:167], v[40:43]
	v_mfma_f32_16x16x32_bf16 v[28:31], v[72:75], v[180:183], v[28:31]
	v_mfma_f32_16x16x32_bf16 v[24:27], v[96:99], v[180:183], v[24:27]
	v_mfma_f32_16x16x32_bf16 v[12:15], v[72:75], v[188:191], v[12:15]
	v_mfma_f32_16x16x32_bf16 v[8:11], v[96:99], v[188:191], v[8:11]
	v_mfma_f32_16x16x32_bf16 v[52:55], v[108:111], v[152:155], v[52:55]
	v_mfma_f32_16x16x32_bf16 v[48:51], v[128:131], v[152:155], v[48:51]
	v_mfma_f32_16x16x32_bf16 v[36:39], v[108:111], v[160:163], v[36:39]
	v_mfma_f32_16x16x32_bf16 v[32:35], v[128:131], v[160:163], v[32:35]
	v_mfma_f32_16x16x32_bf16 v[20:23], v[108:111], v[168:171], v[20:23]
	v_mfma_f32_16x16x32_bf16 v[16:19], v[128:131], v[168:171], v[16:19]
	v_mfma_f32_16x16x32_bf16 v[4:7], v[108:111], v[184:187], v[4:7]
	v_mfma_f32_16x16x32_bf16 v[0:3], v[128:131], v[184:187], v[0:3]
	v_mfma_f32_16x16x32_bf16 v[52:55], v[116:119], v[156:159], v[52:55]
	v_mfma_f32_16x16x32_bf16 v[48:51], v[140:143], v[156:159], v[48:51]
	v_mfma_f32_16x16x32_bf16 v[36:39], v[116:119], v[164:167], v[36:39]
	v_mfma_f32_16x16x32_bf16 v[32:35], v[140:143], v[164:167], v[32:35]
	v_mfma_f32_16x16x32_bf16 v[20:23], v[116:119], v[180:183], v[20:23]
	v_mfma_f32_16x16x32_bf16 v[16:19], v[140:143], v[180:183], v[16:19]
	v_mfma_f32_16x16x32_bf16 v[4:7], v[116:119], v[188:191], v[4:7]
	v_mfma_f32_16x16x32_bf16 v[0:3], v[140:143], v[188:191], v[0:3]
	s_barrier
	s_add_i32 vcc_lo, vcc_lo, 2
	s_add_u32 s81, s81, 0x100
	s_addc_u32 s96, s96, 0
	s_mov_b64 s[78:79], s[82:83]

.Lsk_ready:
	global_load_dwordx4 v[64:67], v192, s[82:83] sc1
	global_load_dwordx4 v[72:75], v192, s[82:83] offset:1024 sc1
	global_load_dwordx4 v[88:91], v192, s[82:83] offset:2048 sc1
	global_load_dwordx4 v[96:99], v192, s[82:83] offset:3072 sc1
	s_add_u32 s78, s82, 0x1000
	s_addc_u32 s79, s83, 0
	global_load_dwordx4 v[108:111], v192, s[78:79] sc1
	global_load_dwordx4 v[116:119], v192, s[78:79] offset:1024 sc1
	global_load_dwordx4 v[128:131], v192, s[78:79] offset:2048 sc1
	global_load_dwordx4 v[140:143], v192, s[78:79] offset:3072 sc1
	s_add_u32 s78, s82, 0x2000
	s_addc_u32 s79, s83, 0
	global_load_dwordx4 v[152:155], v192, s[78:79] sc1
	global_load_dwordx4 v[156:159], v192, s[78:79] offset:1024 sc1
	global_load_dwordx4 v[160:163], v192, s[78:79] offset:2048 sc1
	global_load_dwordx4 v[164:167], v192, s[78:79] offset:3072 sc1
	s_add_u32 s78, s82, 0x3000
	s_addc_u32 s79, s83, 0
	global_load_dwordx4 v[168:171], v192, s[78:79] sc1
	global_load_dwordx4 v[180:183], v192, s[78:79] offset:1024 sc1
	global_load_dwordx4 v[184:187], v192, s[78:79] offset:2048 sc1
	global_load_dwordx4 v[188:191], v192, s[78:79] offset:3072 sc1
	s_add_u32 s78, s82, 0x4000
	s_addc_u32 s79, s83, 0
	global_load_dwordx4 v[194:197], v192, s[78:79] sc1
	global_load_dwordx4 v[198:201], v192, s[78:79] offset:1024 sc1
	global_load_dwordx4 v[202:205], v192, s[78:79] offset:2048 sc1
	global_load_dwordx4 v[206:209], v192, s[78:79] offset:3072 sc1
	s_add_u32 s78, s82, 0x5000
	s_addc_u32 s79, s83, 0
	global_load_dwordx4 v[210:213], v192, s[78:79] sc1
	global_load_dwordx4 v[244:247], v192, s[78:79] offset:1024 sc1
	global_load_dwordx4 v[248:251], v192, s[78:79] offset:2048 sc1
	global_load_dwordx4 v[218:221], v192, s[78:79] offset:3072 sc1
	s_waitcnt vmcnt(16)
	v_pk_add_f32 v[0:1], v[0:1], v[64:65]
	v_pk_add_f32 v[2:3], v[2:3], v[66:67]
	v_pk_add_f32 v[4:5], v[4:5], v[72:73]
	v_pk_add_f32 v[6:7], v[6:7], v[74:75]
	v_pk_add_f32 v[8:9], v[8:9], v[88:89]
	v_pk_add_f32 v[10:11], v[10:11], v[90:91]
	v_pk_add_f32 v[12:13], v[12:13], v[96:97]
	v_pk_add_f32 v[14:15], v[14:15], v[98:99]
	v_pk_add_f32 v[16:17], v[16:17], v[108:109]
	v_pk_add_f32 v[18:19], v[18:19], v[110:111]
	v_pk_add_f32 v[20:21], v[20:21], v[116:117]
	v_pk_add_f32 v[22:23], v[22:23], v[118:119]
	v_pk_add_f32 v[24:25], v[24:25], v[128:129]
	v_pk_add_f32 v[26:27], v[26:27], v[130:131]
	v_pk_add_f32 v[28:29], v[28:29], v[140:141]
	v_pk_add_f32 v[30:31], v[30:31], v[142:143]
	s_add_u32 s78, s82, 0x6000
	s_addc_u32 s79, s83, 0
	global_load_dwordx4 v[64:67], v192, s[78:79] sc1
	global_load_dwordx4 v[72:75], v192, s[78:79] offset:1024 sc1
	global_load_dwordx4 v[88:91], v192, s[78:79] offset:2048 sc1
	global_load_dwordx4 v[96:99], v192, s[78:79] offset:3072 sc1
	s_add_u32 s78, s82, 0x7000
	s_addc_u32 s79, s83, 0
	global_load_dwordx4 v[108:111], v192, s[78:79] sc1
	global_load_dwordx4 v[116:119], v192, s[78:79] offset:1024 sc1
	global_load_dwordx4 v[128:131], v192, s[78:79] offset:2048 sc1
	global_load_dwordx4 v[140:143], v192, s[78:79] offset:3072 sc1
	s_waitcnt vmcnt(16)
	v_pk_add_f32 v[32:33], v[32:33], v[152:153]
	v_pk_add_f32 v[34:35], v[34:35], v[154:155]
	v_pk_add_f32 v[36:37], v[36:37], v[156:157]
	v_pk_add_f32 v[38:39], v[38:39], v[158:159]
	v_pk_add_f32 v[40:41], v[40:41], v[160:161]
	v_pk_add_f32 v[42:43], v[42:43], v[162:163]
	v_pk_add_f32 v[44:45], v[44:45], v[164:165]
	v_pk_add_f32 v[46:47], v[46:47], v[166:167]
	v_pk_add_f32 v[48:49], v[48:49], v[168:169]
	v_pk_add_f32 v[50:51], v[50:51], v[170:171]
	v_pk_add_f32 v[52:53], v[52:53], v[180:181]
	v_pk_add_f32 v[54:55], v[54:55], v[182:183]
	v_pk_add_f32 v[56:57], v[56:57], v[184:185]
	v_pk_add_f32 v[58:59], v[58:59], v[186:187]
	v_pk_add_f32 v[60:61], v[60:61], v[188:189]
	v_pk_add_f32 v[62:63], v[62:63], v[190:191]
	s_add_u32 s78, s82, 0x40000
	s_addc_u32 s79, s83, 0
	global_load_dwordx4 v[152:155], v192, s[78:79] sc1
	global_load_dwordx4 v[156:159], v192, s[78:79] offset:1024 sc1
	global_load_dwordx4 v[160:163], v192, s[78:79] offset:2048 sc1
	global_load_dwordx4 v[164:167], v192, s[78:79] offset:3072 sc1
	s_add_u32 s78, s82, 0x41000
	s_addc_u32 s79, s83, 0
	global_load_dwordx4 v[168:171], v192, s[78:79] sc1
	global_load_dwordx4 v[180:183], v192, s[78:79] offset:1024 sc1
	global_load_dwordx4 v[184:187], v192, s[78:79] offset:2048 sc1
	global_load_dwordx4 v[188:191], v192, s[78:79] offset:3072 sc1
	s_waitcnt vmcnt(16)
	v_pk_add_f32 v[68:69], v[68:69], v[194:195]
	v_pk_add_f32 v[70:71], v[70:71], v[196:197]
	v_pk_add_f32 v[76:77], v[76:77], v[198:199]
	v_pk_add_f32 v[78:79], v[78:79], v[200:201]
	v_pk_add_f32 v[80:81], v[80:81], v[202:203]
	v_pk_add_f32 v[82:83], v[82:83], v[204:205]
	v_pk_add_f32 v[84:85], v[84:85], v[206:207]
	v_pk_add_f32 v[86:87], v[86:87], v[208:209]
	v_pk_add_f32 v[92:93], v[92:93], v[210:211]
	v_pk_add_f32 v[94:95], v[94:95], v[212:213]
	v_pk_add_f32 v[100:101], v[100:101], v[244:245]
	v_pk_add_f32 v[102:103], v[102:103], v[246:247]
	v_pk_add_f32 v[104:105], v[104:105], v[248:249]
	v_pk_add_f32 v[106:107], v[106:107], v[250:251]
	v_pk_add_f32 v[112:113], v[112:113], v[218:219]
	v_pk_add_f32 v[114:115], v[114:115], v[220:221]
	s_add_u32 s78, s82, 0x42000
	s_addc_u32 s79, s83, 0
	global_load_dwordx4 v[194:197], v192, s[78:79] sc1
	global_load_dwordx4 v[198:201], v192, s[78:79] offset:1024 sc1
	global_load_dwordx4 v[202:205], v192, s[78:79] offset:2048 sc1
	global_load_dwordx4 v[206:209], v192, s[78:79] offset:3072 sc1
	s_add_u32 s78, s82, 0x43000
	s_addc_u32 s79, s83, 0
	global_load_dwordx4 v[210:213], v192, s[78:79] sc1
	global_load_dwordx4 v[244:247], v192, s[78:79] offset:1024 sc1
	global_load_dwordx4 v[248:251], v192, s[78:79] offset:2048 sc1
	global_load_dwordx4 v[218:221], v192, s[78:79] offset:3072 sc1
	s_waitcnt vmcnt(16)
	v_pk_add_f32 v[120:121], v[120:121], v[64:65]
	v_pk_add_f32 v[122:123], v[122:123], v[66:67]
	v_pk_add_f32 v[124:125], v[124:125], v[72:73]
	v_pk_add_f32 v[126:127], v[126:127], v[74:75]
	v_pk_add_f32 v[132:133], v[132:133], v[88:89]
	v_pk_add_f32 v[134:135], v[134:135], v[90:91]
	v_pk_add_f32 v[136:137], v[136:137], v[96:97]
	v_pk_add_f32 v[138:139], v[138:139], v[98:99]
	v_pk_add_f32 v[144:145], v[144:145], v[108:109]
	v_pk_add_f32 v[146:147], v[146:147], v[110:111]
	v_pk_add_f32 v[148:149], v[148:149], v[116:117]
	v_pk_add_f32 v[150:151], v[150:151], v[118:119]
	v_pk_add_f32 v[172:173], v[172:173], v[128:129]
	v_pk_add_f32 v[174:175], v[174:175], v[130:131]
	v_pk_add_f32 v[176:177], v[176:177], v[140:141]
	v_pk_add_f32 v[178:179], v[178:179], v[142:143]
	s_add_u32 s78, s82, 0x44000
	s_addc_u32 s79, s83, 0
	global_load_dwordx4 v[64:67], v192, s[78:79] sc1
	global_load_dwordx4 v[72:75], v192, s[78:79] offset:1024 sc1
	global_load_dwordx4 v[88:91], v192, s[78:79] offset:2048 sc1
	global_load_dwordx4 v[96:99], v192, s[78:79] offset:3072 sc1
	s_add_u32 s78, s82, 0x45000
	s_addc_u32 s79, s83, 0
	global_load_dwordx4 v[108:111], v192, s[78:79] sc1
	global_load_dwordx4 v[116:119], v192, s[78:79] offset:1024 sc1
	global_load_dwordx4 v[128:131], v192, s[78:79] offset:2048 sc1
	global_load_dwordx4 v[140:143], v192, s[78:79] offset:3072 sc1
	s_waitcnt vmcnt(16)
	v_pk_add_f32 v[0:1], v[0:1], v[152:153]
	v_pk_add_f32 v[2:3], v[2:3], v[154:155]
	v_pk_add_f32 v[4:5], v[4:5], v[156:157]
	v_pk_add_f32 v[6:7], v[6:7], v[158:159]
	v_pk_add_f32 v[8:9], v[8:9], v[160:161]
	v_pk_add_f32 v[10:11], v[10:11], v[162:163]
	v_pk_add_f32 v[12:13], v[12:13], v[164:165]
	v_pk_add_f32 v[14:15], v[14:15], v[166:167]
	v_pk_add_f32 v[16:17], v[16:17], v[168:169]
	v_pk_add_f32 v[18:19], v[18:19], v[170:171]
	v_pk_add_f32 v[20:21], v[20:21], v[180:181]
	v_pk_add_f32 v[22:23], v[22:23], v[182:183]
	v_pk_add_f32 v[24:25], v[24:25], v[184:185]
	v_pk_add_f32 v[26:27], v[26:27], v[186:187]
	v_pk_add_f32 v[28:29], v[28:29], v[188:189]
	v_pk_add_f32 v[30:31], v[30:31], v[190:191]
	s_add_u32 s78, s82, 0x46000
	s_addc_u32 s79, s83, 0
	global_load_dwordx4 v[152:155], v192, s[78:79] sc1
	global_load_dwordx4 v[156:159], v192, s[78:79] offset:1024 sc1
	global_load_dwordx4 v[160:163], v192, s[78:79] offset:2048 sc1
	global_load_dwordx4 v[164:167], v192, s[78:79] offset:3072 sc1
	s_add_u32 s78, s82, 0x47000
	s_addc_u32 s79, s83, 0
	global_load_dwordx4 v[168:171], v192, s[78:79] sc1
	global_load_dwordx4 v[180:183], v192, s[78:79] offset:1024 sc1
	global_load_dwordx4 v[184:187], v192, s[78:79] offset:2048 sc1
	global_load_dwordx4 v[188:191], v192, s[78:79] offset:3072 sc1
	s_waitcnt vmcnt(16)
	v_pk_add_f32 v[32:33], v[32:33], v[194:195]
	v_pk_add_f32 v[34:35], v[34:35], v[196:197]
	v_pk_add_f32 v[36:37], v[36:37], v[198:199]
	v_pk_add_f32 v[38:39], v[38:39], v[200:201]
	v_pk_add_f32 v[40:41], v[40:41], v[202:203]
	v_pk_add_f32 v[42:43], v[42:43], v[204:205]
	v_pk_add_f32 v[44:45], v[44:45], v[206:207]
	v_pk_add_f32 v[46:47], v[46:47], v[208:209]
	v_pk_add_f32 v[48:49], v[48:49], v[210:211]
	v_pk_add_f32 v[50:51], v[50:51], v[212:213]
	v_pk_add_f32 v[52:53], v[52:53], v[244:245]
	v_pk_add_f32 v[54:55], v[54:55], v[246:247]
	v_pk_add_f32 v[56:57], v[56:57], v[248:249]
	v_pk_add_f32 v[58:59], v[58:59], v[250:251]
	v_pk_add_f32 v[60:61], v[60:61], v[218:219]
	v_pk_add_f32 v[62:63], v[62:63], v[220:221]
	s_add_u32 s78, s82, 0x80000
	s_addc_u32 s79, s83, 0
	global_load_dwordx4 v[194:197], v192, s[78:79] sc1
	global_load_dwordx4 v[198:201], v192, s[78:79] offset:1024 sc1
	global_load_dwordx4 v[202:205], v192, s[78:79] offset:2048 sc1
	global_load_dwordx4 v[206:209], v192, s[78:79] offset:3072 sc1
	s_add_u32 s78, s82, 0x81000
	s_addc_u32 s79, s83, 0
	global_load_dwordx4 v[210:213], v192, s[78:79] sc1
	global_load_dwordx4 v[244:247], v192, s[78:79] offset:1024 sc1
	global_load_dwordx4 v[248:251], v192, s[78:79] offset:2048 sc1
	global_load_dwordx4 v[218:221], v192, s[78:79] offset:3072 sc1
	s_waitcnt vmcnt(16)
	v_pk_add_f32 v[68:69], v[68:69], v[64:65]
	v_pk_add_f32 v[70:71], v[70:71], v[66:67]
	v_pk_add_f32 v[76:77], v[76:77], v[72:73]
	v_pk_add_f32 v[78:79], v[78:79], v[74:75]
	v_pk_add_f32 v[80:81], v[80:81], v[88:89]
	v_pk_add_f32 v[82:83], v[82:83], v[90:91]
	v_pk_add_f32 v[84:85], v[84:85], v[96:97]
	v_pk_add_f32 v[86:87], v[86:87], v[98:99]
	v_pk_add_f32 v[92:93], v[92:93], v[108:109]
	v_pk_add_f32 v[94:95], v[94:95], v[110:111]
	v_pk_add_f32 v[100:101], v[100:101], v[116:117]
	v_pk_add_f32 v[102:103], v[102:103], v[118:119]
	v_pk_add_f32 v[104:105], v[104:105], v[128:129]
	v_pk_add_f32 v[106:107], v[106:107], v[130:131]
	v_pk_add_f32 v[112:113], v[112:113], v[140:141]
	v_pk_add_f32 v[114:115], v[114:115], v[142:143]
	s_add_u32 s78, s82, 0x82000
	s_addc_u32 s79, s83, 0
	global_load_dwordx4 v[64:67], v192, s[78:79] sc1
	global_load_dwordx4 v[72:75], v192, s[78:79] offset:1024 sc1
	global_load_dwordx4 v[88:91], v192, s[78:79] offset:2048 sc1
	global_load_dwordx4 v[96:99], v192, s[78:79] offset:3072 sc1
	s_add_u32 s78, s82, 0x83000
	s_addc_u32 s79, s83, 0
	global_load_dwordx4 v[108:111], v192, s[78:79] sc1
	global_load_dwordx4 v[116:119], v192, s[78:79] offset:1024 sc1
	global_load_dwordx4 v[128:131], v192, s[78:79] offset:2048 sc1
	global_load_dwordx4 v[140:143], v192, s[78:79] offset:3072 sc1
	s_waitcnt vmcnt(16)
	v_pk_add_f32 v[120:121], v[120:121], v[152:153]
	v_pk_add_f32 v[122:123], v[122:123], v[154:155]
	v_pk_add_f32 v[124:125], v[124:125], v[156:157]
	v_pk_add_f32 v[126:127], v[126:127], v[158:159]
	v_pk_add_f32 v[132:133], v[132:133], v[160:161]
	v_pk_add_f32 v[134:135], v[134:135], v[162:163]
	v_pk_add_f32 v[136:137], v[136:137], v[164:165]
	v_pk_add_f32 v[138:139], v[138:139], v[166:167]
	v_pk_add_f32 v[144:145], v[144:145], v[168:169]
	v_pk_add_f32 v[146:147], v[146:147], v[170:171]
	v_pk_add_f32 v[148:149], v[148:149], v[180:181]
	v_pk_add_f32 v[150:151], v[150:151], v[182:183]
	v_pk_add_f32 v[172:173], v[172:173], v[184:185]
	v_pk_add_f32 v[174:175], v[174:175], v[186:187]
	v_pk_add_f32 v[176:177], v[176:177], v[188:189]
	v_pk_add_f32 v[178:179], v[178:179], v[190:191]
	s_add_u32 s78, s82, 0x84000
	s_addc_u32 s79, s83, 0
	global_load_dwordx4 v[152:155], v192, s[78:79] sc1
	global_load_dwordx4 v[156:159], v192, s[78:79] offset:1024 sc1
	global_load_dwordx4 v[160:163], v192, s[78:79] offset:2048 sc1
	global_load_dwordx4 v[164:167], v192, s[78:79] offset:3072 sc1
	s_add_u32 s78, s82, 0x85000
	s_addc_u32 s79, s83, 0
	global_load_dwordx4 v[168:171], v192, s[78:79] sc1
	global_load_dwordx4 v[180:183], v192, s[78:79] offset:1024 sc1
	global_load_dwordx4 v[184:187], v192, s[78:79] offset:2048 sc1
	global_load_dwordx4 v[188:191], v192, s[78:79] offset:3072 sc1
	s_waitcnt vmcnt(16)
	v_pk_add_f32 v[0:1], v[0:1], v[194:195]
	v_pk_add_f32 v[2:3], v[2:3], v[196:197]
	v_pk_add_f32 v[4:5], v[4:5], v[198:199]
	v_pk_add_f32 v[6:7], v[6:7], v[200:201]
	v_pk_add_f32 v[8:9], v[8:9], v[202:203]
	v_pk_add_f32 v[10:11], v[10:11], v[204:205]
	v_pk_add_f32 v[12:13], v[12:13], v[206:207]
	v_pk_add_f32 v[14:15], v[14:15], v[208:209]
	v_pk_add_f32 v[16:17], v[16:17], v[210:211]
	v_pk_add_f32 v[18:19], v[18:19], v[212:213]
	v_pk_add_f32 v[20:21], v[20:21], v[244:245]
	v_pk_add_f32 v[22:23], v[22:23], v[246:247]
	v_pk_add_f32 v[24:25], v[24:25], v[248:249]
	v_pk_add_f32 v[26:27], v[26:27], v[250:251]
	v_pk_add_f32 v[28:29], v[28:29], v[218:219]
	v_pk_add_f32 v[30:31], v[30:31], v[220:221]
	s_add_u32 s78, s82, 0x86000
	s_addc_u32 s79, s83, 0
	global_load_dwordx4 v[194:197], v192, s[78:79] sc1
	global_load_dwordx4 v[198:201], v192, s[78:79] offset:1024 sc1
	global_load_dwordx4 v[202:205], v192, s[78:79] offset:2048 sc1
	global_load_dwordx4 v[206:209], v192, s[78:79] offset:3072 sc1
	s_add_u32 s78, s82, 0x87000
	s_addc_u32 s79, s83, 0
	global_load_dwordx4 v[210:213], v192, s[78:79] sc1
	global_load_dwordx4 v[244:247], v192, s[78:79] offset:1024 sc1
	global_load_dwordx4 v[248:251], v192, s[78:79] offset:2048 sc1
	global_load_dwordx4 v[218:221], v192, s[78:79] offset:3072 sc1
	s_waitcnt vmcnt(16)
	v_pk_add_f32 v[32:33], v[32:33], v[64:65]
	v_pk_add_f32 v[34:35], v[34:35], v[66:67]
	v_pk_add_f32 v[36:37], v[36:37], v[72:73]
	v_pk_add_f32 v[38:39], v[38:39], v[74:75]
	v_pk_add_f32 v[40:41], v[40:41], v[88:89]
	v_pk_add_f32 v[42:43], v[42:43], v[90:91]
	v_pk_add_f32 v[44:45], v[44:45], v[96:97]
	v_pk_add_f32 v[46:47], v[46:47], v[98:99]
	v_pk_add_f32 v[48:49], v[48:49], v[108:109]
	v_pk_add_f32 v[50:51], v[50:51], v[110:111]
	v_pk_add_f32 v[52:53], v[52:53], v[116:117]
	v_pk_add_f32 v[54:55], v[54:55], v[118:119]
	v_pk_add_f32 v[56:57], v[56:57], v[128:129]
	v_pk_add_f32 v[58:59], v[58:59], v[130:131]
	v_pk_add_f32 v[60:61], v[60:61], v[140:141]
	v_pk_add_f32 v[62:63], v[62:63], v[142:143]
	s_waitcnt vmcnt(8)
	v_pk_add_f32 v[68:69], v[68:69], v[152:153]
	v_pk_add_f32 v[70:71], v[70:71], v[154:155]
	v_pk_add_f32 v[76:77], v[76:77], v[156:157]
	v_pk_add_f32 v[78:79], v[78:79], v[158:159]
	v_pk_add_f32 v[80:81], v[80:81], v[160:161]
	v_pk_add_f32 v[82:83], v[82:83], v[162:163]
	v_pk_add_f32 v[84:85], v[84:85], v[164:165]
	v_pk_add_f32 v[86:87], v[86:87], v[166:167]
	v_pk_add_f32 v[92:93], v[92:93], v[168:169]
	v_pk_add_f32 v[94:95], v[94:95], v[170:171]
	v_pk_add_f32 v[100:101], v[100:101], v[180:181]
	v_pk_add_f32 v[102:103], v[102:103], v[182:183]
	v_pk_add_f32 v[104:105], v[104:105], v[184:185]
	v_pk_add_f32 v[106:107], v[106:107], v[186:187]
	v_pk_add_f32 v[112:113], v[112:113], v[188:189]
	v_pk_add_f32 v[114:115], v[114:115], v[190:191]
	s_waitcnt vmcnt(0)
	v_pk_add_f32 v[120:121], v[120:121], v[194:195]
	v_pk_add_f32 v[122:123], v[122:123], v[196:197]
	v_pk_add_f32 v[124:125], v[124:125], v[198:199]
	v_pk_add_f32 v[126:127], v[126:127], v[200:201]
	v_pk_add_f32 v[132:133], v[132:133], v[202:203]
	v_pk_add_f32 v[134:135], v[134:135], v[204:205]
	v_pk_add_f32 v[136:137], v[136:137], v[206:207]
	v_pk_add_f32 v[138:139], v[138:139], v[208:209]
	v_pk_add_f32 v[144:145], v[144:145], v[210:211]
	v_pk_add_f32 v[146:147], v[146:147], v[212:213]
	v_pk_add_f32 v[148:149], v[148:149], v[244:245]
	v_pk_add_f32 v[150:151], v[150:151], v[246:247]
	v_pk_add_f32 v[172:173], v[172:173], v[248:249]
	v_pk_add_f32 v[174:175], v[174:175], v[250:251]
	v_pk_add_f32 v[176:177], v[176:177], v[218:219]
	v_pk_add_f32 v[178:179], v[178:179], v[220:221]

.LBB0_1313:
.LBB0_1337:
	s_waitcnt lgkmcnt(0)
	v_readlane_b32 s6, v255, 6
	v_readlane_b32 s0, v255, 8
	v_readlane_b32 s7, v255, 7
	s_waitcnt vmcnt(0)
	s_barrier
	s_mov_b64 s[4:5], exec
	v_readlane_b32 s2, v255, 9
	v_readlane_b32 s3, v255, 10
	s_and_b64 s[2:3], s[4:5], s[2:3]
	s_mov_b64 exec, s[2:3]
	s_cbranch_execnz .LBB0_1338
	s_getpc_b64 s[98:99]

.LBB0_1347:
	s_cmp_lt_u32 s2, 0x400001
	s_mov_b64 s[20:21], 0
	s_cselect_b64 s[68:69], -1, 0
	s_and_b64 vcc, exec, s[68:69]
	s_cbranch_vccnz .LBB0_1344
	s_branch .LBB0_1340
.LBB0_1351:
	s_andn2_b64 vcc, exec, s[20:21]
	s_cbranch_vccz .LBB0_1355
	s_mov_b64 s[10:11], exec
	v_mbcnt_lo_u32_b32 v16, s10, 0
	v_mbcnt_hi_u32_b32 v16, s11, v16
	v_cmp_eq_u32_e32 vcc, 0, v16
	s_and_saveexec_b64 s[8:9], vcc
	s_cbranch_execz .LBB0_1354
	s_bcnt1_i32_b64 s1, s[10:11]
	v_mov_b32_e32 v16, s1
	global_atomic_add v217, v16, s[6:7] offset:512
